# prompt attention PV: transposed V reads issued one MFMA ahead (two alternating operand sets, lgkmcnt(2)) instead of read-wait-MFMA
# speedup vs baseline: 1.0104x; 1.0104x over previous
; #define LAS __attribute__((address_space(3)))
; #define MFMA32(a, b, c) __builtin_amdgcn_mfma_f32_32x32x16_bf16((a), (b), (c), 0, 0, 0)
; __device__ __forceinline__ void attn_run(LAS unsigned char* lds, const Params& p, const bf16_t* P, bf16_t* Y, float* ssa, int l, int t0, int t1, int wave) {
;     ...
;             for (int T = 0; T < 6; ++T)
;                 if (T >= T0) {
;                     const int prow = 64 * ((T >> 1) == 0 ? sl0 : ((T >> 1) == 1 ? sl1 : sl2)) + 32 * (T & 1);
; #pragma unroll
;                     for (int s = 0; s < 2; ++s) {
;                         const bf16x8 xs = pack_step(st[T], s);
; #pragma unroll
;                         for (int dt = 0; dt < 2; ++dt) {
;                             const LAS bf16_t* vp = VT + (prow + 16 * s + 4 * h + ((lane & 15) >> 2)) * 72 + 32 * dt + 16 * ((lane >> 4) & 1) + 4 * (lane & 3);
;                             const s16x4 lo = __builtin_amdgcn_ds_read_tr16_b64_v4i16((LAS s16x4*)vp), hi = __builtin_amdgcn_ds_read_tr16_b64_v4i16((LAS s16x4*)(vp + 8 * 72));
;                             const bf16x8 pa = __builtin_shufflevector(lo, hi, 0, 1, 2, 3, 4, 5, 6, 7);
;                             o[dt] = MFMA32(pa, xs, o[dt]);
;                         }
;                     }
;                 }
.LBB0_350:
	v_add_u32_e32 v0, s29, v169
	v_mad_u64_u32 v[10:11], s[12:13], v0, s89, v[158:159]
	ds_read_b64_tr_b16 v[6:7], v10 offset:27648
	ds_read_b64_tr_b16 v[8:9], v10 offset:28800
	v_cvt_pk_bf16_f32 v2, v179, v193
	v_cvt_pk_bf16_f32 v3, v198, v202
	v_cvt_pk_bf16_f32 v4, v213, v220
	v_cvt_pk_bf16_f32 v5, v225, v227
	ds_read_b64_tr_b16 v[234:235], v10 offset:27712
	ds_read_b64_tr_b16 v[236:237], v10 offset:28864
	s_waitcnt lgkmcnt(2)
	s_nop 0
	v_mfma_f32_32x32x16_bf16 v[32:47], v[6:9], v[2:5], v[32:47]
	ds_read_b64_tr_b16 v[6:7], v10 offset:29952
	ds_read_b64_tr_b16 v[8:9], v10 offset:31104
	s_waitcnt lgkmcnt(2)
	v_mfma_f32_32x32x16_bf16 v[16:31], v[234:237], v[2:5], v[16:31]
	v_cvt_pk_bf16_f32 v2, v180, v194
	v_cvt_pk_bf16_f32 v3, v199, v203
	v_cvt_pk_bf16_f32 v4, v214, v221
	v_cvt_pk_bf16_f32 v5, v226, v228
	ds_read_b64_tr_b16 v[234:235], v10 offset:30016
	ds_read_b64_tr_b16 v[236:237], v10 offset:31168
	s_waitcnt lgkmcnt(2)
	s_nop 0
	v_mfma_f32_32x32x16_bf16 v[32:47], v[6:9], v[2:5], v[32:47]
	s_waitcnt lgkmcnt(0)
	v_mfma_f32_32x32x16_bf16 v[16:31], v[234:237], v[2:5], v[16:31]

; #define LAS __attribute__((address_space(3)))
; #define MFMA32(a, b, c) __builtin_amdgcn_mfma_f32_32x32x16_bf16((a), (b), (c), 0, 0, 0)
; __device__ __forceinline__ void attn_run(LAS unsigned char* lds, const Params& p, const bf16_t* P, bf16_t* Y, float* ssa, int l, int t0, int t1, int wave) {
;     ...
;             for (int T = 0; T < 6; ++T)
;                 if (T >= T0) {
;                     const int prow = 64 * ((T >> 1) == 0 ? sl0 : ((T >> 1) == 1 ? sl1 : sl2)) + 32 * (T & 1);
; #pragma unroll
;                     for (int s = 0; s < 2; ++s) {
;                         const bf16x8 xs = pack_step(st[T], s);
; #pragma unroll
;                         for (int dt = 0; dt < 2; ++dt) {
;                             const LAS bf16_t* vp = VT + (prow + 16 * s + 4 * h + ((lane & 15) >> 2)) * 72 + 32 * dt + 16 * ((lane >> 4) & 1) + 4 * (lane & 3);
;                             const s16x4 lo = __builtin_amdgcn_ds_read_tr16_b64_v4i16((LAS s16x4*)vp), hi = __builtin_amdgcn_ds_read_tr16_b64_v4i16((LAS s16x4*)(vp + 8 * 72));
;                             const bf16x8 pa = __builtin_shufflevector(lo, hi, 0, 1, 2, 3, 4, 5, 6, 7);
;                             o[dt] = MFMA32(pa, xs, o[dt]);
;                         }
;                     }
;                 }
;             float ss = 0.f;
;             bf16_t* yp = Y + qrow * DM + head * 64 + 8 * h;
; #pragma unroll
;             for (int dt = 0; dt < 2; ++dt)
; #pragma unroll
;                 for (int pr = 0; pr < 2; ++pr) {
;                     float a[4], bq[4];
; #pragma unroll
;                     for (int k = 0; k < 4; ++k) { a[k] = o[dt][8 * pr + k] * inv; bq[k] = o[dt][8 * pr + 4 + k] * inv; }
;                     ss += ((a[0] * a[0] + a[1] * a[1]) + (a[2] * a[2] + a[3] * a[3])) + ((bq[0] * bq[0] + bq[1] * bq[1]) + (bq[2] * bq[2] + bq[3] * bq[3]));
; #pragma unroll
;                     for (int k = 0; k < 4; ++k) swap_halves(a[k], bq[k]);
;                     const u32x4 gw = gwv[2 * dt + pr];
;                     u32x4 w; w.x = pk2(a[0] * bf_lo(gw.x), a[1] * bf_hi(gw.x)); w.y = pk2(a[2] * bf_lo(gw.y), a[3] * bf_hi(gw.y));
;                     w.z = pk2(bq[0] * bf_lo(gw.z), bq[1] * bf_hi(gw.z)); w.w = pk2(bq[2] * bf_lo(gw.w), bq[3] * bf_hi(gw.w));
;                     *(u32x4*)(yp + 32 * dt + 16 * pr) = w;
;                 }
.LBB0_353:
	v_add_u32_e32 v0, s26, v169
	v_mad_u64_u32 v[10:11], s[12:13], v0, s89, v[158:159]
	ds_read_b64_tr_b16 v[6:7], v10 offset:27648
	ds_read_b64_tr_b16 v[8:9], v10 offset:28800
	v_cvt_pk_bf16_f32 v2, v94, v97
	v_cvt_pk_bf16_f32 v3, v174, v181
	v_cvt_pk_bf16_f32 v4, v200, v204
	v_cvt_pk_bf16_f32 v5, v208, v215
	ds_read_b64_tr_b16 v[234:235], v10 offset:27712
	ds_read_b64_tr_b16 v[236:237], v10 offset:28864
	s_waitcnt lgkmcnt(2)
	s_nop 0
	v_mfma_f32_32x32x16_bf16 v[32:47], v[6:9], v[2:5], v[32:47]
	ds_read_b64_tr_b16 v[6:7], v10 offset:29952
	ds_read_b64_tr_b16 v[8:9], v10 offset:31104
	s_waitcnt lgkmcnt(2)
	v_mfma_f32_32x32x16_bf16 v[16:31], v[234:237], v[2:5], v[16:31]
	v_cvt_pk_bf16_f32 v2, v95, v163
	v_cvt_pk_bf16_f32 v3, v175, v182
	v_cvt_pk_bf16_f32 v4, v201, v205
	v_cvt_pk_bf16_f32 v5, v209, v216
	ds_read_b64_tr_b16 v[234:235], v10 offset:30016
	ds_read_b64_tr_b16 v[236:237], v10 offset:31168
	s_waitcnt lgkmcnt(2)
	s_nop 0
	v_mfma_f32_32x32x16_bf16 v[32:47], v[6:9], v[2:5], v[32:47]
	s_waitcnt lgkmcnt(0)
	v_mfma_f32_32x32x16_bf16 v[16:31], v[234:237], v[2:5], v[16:31]
.LBB0_354:
	v_add_u32_e32 v6, s25, v168
	v_sub_f32_e32 v2, v66, v68
	v_mad_u64_u32 v[10:11], s[12:13], v6, s89, v[158:159]
	v_exp_f32_e32 v2, v2
	ds_read_b64_tr_b16 v[6:7], v10 offset:27648
	ds_read_b64_tr_b16 v[8:9], v10 offset:28800
	s_waitcnt lgkmcnt(2)
	v_add_f32_e32 v0, v69, v70
	v_cvt_pk_bf16_f32 v3, v63, v79
	v_add_f32_e32 v0, v2, v0
	v_cvt_pk_bf16_f32 v2, v56, v60
	v_cvt_pk_bf16_f32 v4, v144, v145
	v_cvt_pk_bf16_f32 v5, v142, v143
	s_lshl_b32 s44, s10, 1
	s_waitcnt lgkmcnt(0)
	v_mfma_f32_32x32x16_bf16 v[32:47], v[6:9], v[2:5], v[32:47]
	ds_read_b64_tr_b16 v[6:7], v10 offset:27712
	ds_read_b64_tr_b16 v[8:9], v10 offset:28864
	ds_read_b64_tr_b16 v[234:235], v10 offset:29952
	ds_read_b64_tr_b16 v[236:237], v10 offset:31104
	s_waitcnt lgkmcnt(2)
	v_mfma_f32_32x32x16_bf16 v[16:31], v[6:9], v[2:5], v[16:31]
	v_cvt_pk_bf16_f32 v2, v59, v64
	v_cvt_pk_bf16_f32 v3, v78, v96
	v_cvt_pk_bf16_f32 v4, v92, v93
	v_cvt_pk_bf16_f32 v5, v90, v91
	ds_read_b64_tr_b16 v[6:7], v10 offset:30016
	ds_read_b64_tr_b16 v[8:9], v10 offset:31168
	s_waitcnt lgkmcnt(2)
	s_nop 0
	v_mfma_f32_32x32x16_bf16 v[32:47], v[234:237], v[2:5], v[32:47]
	s_waitcnt lgkmcnt(0)
	v_mfma_f32_32x32x16_bf16 v[16:31], v[6:9], v[2:5], v[16:31]
	v_add_u32_e32 v6, s25, v169
	v_mad_u64_u32 v[10:11], s[12:13], v6, s89, v[158:159]
	ds_read_b64_tr_b16 v[6:7], v10 offset:27648
	ds_read_b64_tr_b16 v[8:9], v10 offset:28800
	v_cvt_pk_bf16_f32 v2, v52, v54
	v_cvt_pk_bf16_f32 v3, v57, v61
	v_cvt_pk_bf16_f32 v4, v81, v84
	v_cvt_pk_bf16_f32 v5, v82, v83
	ds_read_b64_tr_b16 v[234:235], v10 offset:27712
	ds_read_b64_tr_b16 v[236:237], v10 offset:28864
	s_waitcnt lgkmcnt(2)
	s_nop 0
	v_mfma_f32_32x32x16_bf16 v[32:47], v[6:9], v[2:5], v[32:47]
	ds_read_b64_tr_b16 v[6:7], v10 offset:29952
	ds_read_b64_tr_b16 v[8:9], v10 offset:31104
	s_waitcnt lgkmcnt(2)
	v_mfma_f32_32x32x16_bf16 v[16:31], v[234:237], v[2:5], v[16:31]
	v_cvt_pk_bf16_f32 v2, v48, v49
	v_cvt_pk_bf16_f32 v3, v51, v53
	v_cvt_pk_bf16_f32 v4, v58, v62
	v_cvt_pk_bf16_f32 v5, v65, v67
	ds_read_b64_tr_b16 v[234:235], v10 offset:30016
	ds_read_b64_tr_b16 v[236:237], v10 offset:31168
	s_waitcnt lgkmcnt(2)
	s_nop 0
	v_mfma_f32_32x32x16_bf16 v[32:47], v[6:9], v[2:5], v[32:47]
	s_waitcnt lgkmcnt(0)
	v_mfma_f32_32x32x16_bf16 v[16:31], v[234:237], v[2:5], v[16:31]
	v_div_scale_f32 v2, s[12:13], v0, v0, 1.0
	v_rcp_f32_e32 v3, v2
	s_nop 0
	v_fma_f32 v4, -v2, v3, 1.0
	v_fmac_f32_e32 v3, v4, v3
	v_div_scale_f32 v4, vcc, 1.0, v0, 1.0
	v_mul_f32_e32 v5, v4, v3
	v_fma_f32 v6, -v2, v5, v4
	v_fmac_f32_e32 v5, v6, v3
	v_fma_f32 v2, -v2, v5, v4
	v_div_fmas_f32 v2, v2, v3, v5
	v_div_fixup_f32 v0, v2, v0, 1.0
	v_mul_f32_e32 v5, v0, v33
	v_mul_f32_e32 v9, v0, v35
	v_mul_f32_e32 v4, v0, v32
	v_mul_f32_e32 v8, v0, v34
	v_mul_f32_e32 v12, v5, v5
	v_mul_f32_e32 v13, v9, v9
	v_mul_f32_e32 v7, v0, v37
	v_mul_f32_e32 v11, v0, v39
	v_fmac_f32_e32 v12, v4, v4
	v_fmac_f32_e32 v13, v8, v8
	v_mul_f32_e32 v6, v0, v36
	v_mul_f32_e32 v10, v0, v38
	v_add_f32_e32 v12, v12, v13
	v_mul_f32_e32 v13, v7, v7
	v_mul_f32_e32 v14, v11, v11
	v_fmac_f32_e32 v13, v6, v6
	v_fmac_f32_e32 v14, v10, v10
	v_add_f32_e32 v13, v13, v14
	v_permlane32_swap_b32_e32 v4, v6
	v_permlane32_swap_b32_e32 v5, v7
	v_add_f32_e32 v14, v13, v12
	v_permlane32_swap_b32_e32 v8, v10
	v_permlane32_swap_b32_e32 v9, v11
	v_lshlrev_b32_e32 v12, 16, v134
	v_and_b32_e32 v13, 0xffff0000, v134
	v_pk_mul_f32 v[4:5], v[12:13], v[4:5]
	v_lshlrev_b32_e32 v12, 16, v135
	v_and_b32_e32 v13, 0xffff0000, v135
	v_pk_mul_f32 v[8:9], v[12:13], v[8:9]
	v_lshlrev_b64 v[2:3], 12, v[164:165]
	v_cvt_pk_bf16_f32 v4, v4, v5
	v_cvt_pk_bf16_f32 v5, v8, v9
	v_lshlrev_b32_e32 v8, 16, v136
	v_and_b32_e32 v9, 0xffff0000, v136
	v_lshl_add_u64 v[2:3], s[36:37], 0, v[2:3]
	v_pk_mul_f32 v[6:7], v[8:9], v[6:7]
	v_lshlrev_b32_e32 v8, 16, v137
	v_and_b32_e32 v9, 0xffff0000, v137
	v_lshl_add_u64 v[2:3], v[2:3], 0, s[44:45]
	v_pk_mul_f32 v[8:9], v[8:9], v[10:11]
	v_lshl_add_u64 v[2:3], v[156:157], 1, v[2:3]
	v_cvt_pk_bf16_f32 v6, v6, v7
	v_cvt_pk_bf16_f32 v7, v8, v9
	global_store_dwordx4 v[2:3], v[4:7], off
	v_mul_f32_e32 v9, v0, v43
	v_mul_f32_e32 v8, v0, v42
	v_mul_f32_e32 v5, v0, v41
	v_mul_f32_e32 v4, v0, v40
	v_mul_f32_e32 v12, v5, v5
	v_mul_f32_e32 v13, v9, v9
; #define LAS __attribute__((address_space(3)))
; __device__ __forceinline__ void attn_run(LAS unsigned char* lds, const Params& p, const bf16_t* P, bf16_t* Y, float* ssa, int l, int t0, int t1, int wave) {
;     ...
;             for (int T = 0; T < 6; ++T)
;                 if (T >= T0) {
;                     const int prow = 64 * ((T >> 1) == 0 ? sl0 : ((T >> 1) == 1 ? sl1 : sl2)) + 32 * (T & 1);
; #pragma unroll
;                     for (int s = 0; s < 2; ++s) {
;                         const bf16x8 xs = pack_step(st[T], s);
; #pragma unroll
;                         for (int dt = 0; dt < 2; ++dt) {
;                             const LAS bf16_t* vp = VT + (prow + 16 * s + 4 * h + ((lane & 15) >> 2)) * 72 + 32 * dt + 16 * ((lane >> 4) & 1) + 4 * (lane & 3);
;                             const s16x4 lo = __builtin_amdgcn_ds_read_tr16_b64_v4i16((LAS s16x4*)vp), hi = __builtin_amdgcn_ds_read_tr16_b64_v4i16((LAS s16x4*)(vp + 8 * 72));
;                             const bf16x8 pa = __builtin_shufflevector(lo, hi, 0, 1, 2, 3, 4, 5, 6, 7);
;                             o[dt] = MFMA32(pa, xs, o[dt]);
;                         }
;                     }
;                 }
;             float ss = 0.f;
;             bf16_t* yp = Y + qrow * DM + head * 64 + 8 * h;
; #pragma unroll
;             for (int dt = 0; dt < 2; ++dt)
; #pragma unroll
;                 for (int pr = 0; pr < 2; ++pr) {
;                     float a[4], bq[4];
; #pragma unroll
;                     for (int k = 0; k < 4; ++k) { a[k] = o[dt][8 * pr + k] * inv; bq[k] = o[dt][8 * pr + 4 + k] * inv; }
;                     ss += ((a[0] * a[0] + a[1] * a[1]) + (a[2] * a[2] + a[3] * a[3])) + ((bq[0] * bq[0] + bq[1] * bq[1]) + (bq[2] * bq[2] + bq[3] * bq[3]));
; #pragma unroll
;                     for (int k = 0; k < 4; ++k) swap_halves(a[k], bq[k]);
;                     const u32x4 gw = gwv[2 * dt + pr];
;                     u32x4 w; w.x = pk2(a[0] * bf_lo(gw.x), a[1] * bf_hi(gw.x)); w.y = pk2(a[2] * bf_lo(gw.y), a[3] * bf_hi(gw.y));
;                     w.z = pk2(bq[0] * bf_lo(gw.z), bq[1] * bf_hi(gw.z)); w.w = pk2(bq[2] * bf_lo(gw.w), bq[3] * bf_hi(gw.w));
;                     *(u32x4*)(yp + 32 * dt + 16 * pr) = w;
;                 }
;             ss += __shfl_xor(ss, 32);
;             if (h == 0) ssa[qrow * 16 + head] = ss;
	v_mul_f32_e32 v7, v0, v45
	v_mul_f32_e32 v11, v0, v47
	v_fmac_f32_e32 v12, v4, v4
	v_fmac_f32_e32 v13, v8, v8
	v_mul_f32_e32 v6, v0, v44
	v_mul_f32_e32 v10, v0, v46
	v_add_f32_e32 v12, v12, v13
	v_mul_f32_e32 v13, v7, v7
	v_mul_f32_e32 v15, v11, v11
	v_fmac_f32_e32 v13, v6, v6
	v_fmac_f32_e32 v15, v10, v10
	v_add_f32_e32 v13, v13, v15
	v_add_f32_e32 v12, v13, v12
	v_permlane32_swap_b32_e32 v4, v6
	v_permlane32_swap_b32_e32 v5, v7
	v_permlane32_swap_b32_e32 v8, v10
	v_permlane32_swap_b32_e32 v9, v11
	v_add_f32_e32 v14, v14, v12
	v_lshlrev_b32_e32 v12, 16, v130
	v_and_b32_e32 v13, 0xffff0000, v130
	v_pk_mul_f32 v[4:5], v[12:13], v[4:5]
	v_lshlrev_b32_e32 v12, 16, v131
	v_and_b32_e32 v13, 0xffff0000, v131
	v_pk_mul_f32 v[8:9], v[12:13], v[8:9]
	v_cvt_pk_bf16_f32 v4, v4, v5
	v_cvt_pk_bf16_f32 v5, v8, v9
	v_lshlrev_b32_e32 v8, 16, v132
	v_and_b32_e32 v9, 0xffff0000, v132
	v_pk_mul_f32 v[6:7], v[8:9], v[6:7]
	v_lshlrev_b32_e32 v8, 16, v133
	v_and_b32_e32 v9, 0xffff0000, v133
	v_pk_mul_f32 v[8:9], v[8:9], v[10:11]
	v_cvt_pk_bf16_f32 v6, v6, v7
	v_cvt_pk_bf16_f32 v7, v8, v9
	global_store_dwordx4 v[2:3], v[4:7], off offset:32
	v_mul_f32_e32 v9, v0, v19
	v_mul_f32_e32 v8, v0, v18
	v_mul_f32_e32 v5, v0, v17
	v_mul_f32_e32 v4, v0, v16
	v_mul_f32_e32 v12, v5, v5
	v_mul_f32_e32 v13, v9, v9
	v_mul_f32_e32 v7, v0, v21
	v_mul_f32_e32 v11, v0, v23
	v_fmac_f32_e32 v12, v4, v4
	v_fmac_f32_e32 v13, v8, v8
	v_mul_f32_e32 v6, v0, v20
	v_mul_f32_e32 v10, v0, v22
	v_add_f32_e32 v12, v12, v13
	v_mul_f32_e32 v13, v7, v7
	v_mul_f32_e32 v15, v11, v11
	v_fmac_f32_e32 v13, v6, v6
	v_fmac_f32_e32 v15, v10, v10
	v_add_f32_e32 v13, v13, v15
	v_add_f32_e32 v12, v13, v12
	v_permlane32_swap_b32_e32 v4, v6
	v_permlane32_swap_b32_e32 v5, v7
	v_permlane32_swap_b32_e32 v8, v10
	v_permlane32_swap_b32_e32 v9, v11
	v_add_f32_e32 v14, v14, v12
	v_lshlrev_b32_e32 v12, 16, v126
	v_and_b32_e32 v13, 0xffff0000, v126
	v_pk_mul_f32 v[4:5], v[12:13], v[4:5]
	v_lshlrev_b32_e32 v12, 16, v127
	v_and_b32_e32 v13, 0xffff0000, v127
	v_pk_mul_f32 v[8:9], v[12:13], v[8:9]
	v_cvt_pk_bf16_f32 v4, v4, v5
	v_cvt_pk_bf16_f32 v5, v8, v9
	v_lshlrev_b32_e32 v8, 16, v128
	v_and_b32_e32 v9, 0xffff0000, v128
	v_pk_mul_f32 v[6:7], v[8:9], v[6:7]
	v_lshlrev_b32_e32 v8, 16, v129
	v_and_b32_e32 v9, 0xffff0000, v129
	v_pk_mul_f32 v[8:9], v[8:9], v[10:11]
	v_cvt_pk_bf16_f32 v6, v6, v7
	v_cvt_pk_bf16_f32 v7, v8, v9
	global_store_dwordx4 v[2:3], v[4:7], off offset:64
	v_mul_f32_e32 v9, v0, v27
	v_mul_f32_e32 v8, v0, v26
	v_mul_f32_e32 v5, v0, v25
	v_mul_f32_e32 v4, v0, v24
	v_mul_f32_e32 v6, v0, v28
	v_mul_f32_e32 v7, v0, v29
	v_mul_f32_e32 v10, v0, v30
	v_mul_f32_e32 v11, v0, v31
	v_mul_f32_e32 v0, v5, v5
	v_mul_f32_e32 v12, v9, v9
	v_fmac_f32_e32 v0, v4, v4
	v_fmac_f32_e32 v12, v8, v8
	v_add_f32_e32 v0, v0, v12
	v_mul_f32_e32 v12, v7, v7
	v_mul_f32_e32 v13, v11, v11
	v_fmac_f32_e32 v12, v6, v6
	v_fmac_f32_e32 v13, v10, v10
	v_add_f32_e32 v12, v12, v13
	v_permlane32_swap_b32_e32 v4, v6
	v_permlane32_swap_b32_e32 v5, v7
	v_add_f32_e32 v0, v12, v0
	v_permlane32_swap_b32_e32 v8, v10
	v_permlane32_swap_b32_e32 v9, v11
	v_lshlrev_b32_e32 v12, 16, v122
	v_and_b32_e32 v13, 0xffff0000, v122
	v_pk_mul_f32 v[4:5], v[12:13], v[4:5]
	v_lshlrev_b32_e32 v12, 16, v123
	v_and_b32_e32 v13, 0xffff0000, v123
	v_pk_mul_f32 v[8:9], v[12:13], v[8:9]
	v_cvt_pk_bf16_f32 v4, v4, v5
	v_cvt_pk_bf16_f32 v5, v8, v9
	v_lshlrev_b32_e32 v8, 16, v124
	v_and_b32_e32 v9, 0xffff0000, v124
	v_pk_mul_f32 v[6:7], v[8:9], v[6:7]
	v_lshlrev_b32_e32 v8, 16, v125
	v_and_b32_e32 v9, 0xffff0000, v125
	v_pk_mul_f32 v[8:9], v[8:9], v[10:11]
	v_add_f32_e32 v0, v0, v14
	v_cvt_pk_bf16_f32 v6, v6, v7
	v_cvt_pk_bf16_f32 v7, v8, v9
	global_store_dwordx4 v[2:3], v[4:7], off offset:96
	ds_bpermute_b32 v2, v167, v0
	s_and_saveexec_b64 s[10:11], s[40:41]
	s_cbranch_execz .LBB0_324
	v_readlane_b32 s4, v253, 15
	v_lshlrev_b64 v[4:5], 6, v[164:165]
	v_readlane_b32 s5, v253, 16
	s_lshl_b32 s44, s24, 2
	s_waitcnt lgkmcnt(0)
	v_add_f32_e32 v0, v0, v2
	v_lshl_add_u64 v[4:5], s[4:5], 0, v[4:5]
	v_lshl_add_u64 v[4:5], v[4:5], 0, s[44:45]
	global_store_dword v[4:5], v0, off
	s_branch .LBB0_324
.LBB0_356:
	v_add_u32_e32 v0, s26, v168
	v_mad_u64_u32 v[10:11], s[10:11], v0, s89, v[158:159]
	ds_read_b64_tr_b16 v[6:7], v10 offset:27648
	ds_read_b64_tr_b16 v[8:9], v10 offset:28800
	v_cvt_pk_bf16_f32 v2, v172, v177
	v_cvt_pk_bf16_f32 v3, v183, v196
	v_cvt_pk_bf16_f32 v4, v206, v211
	v_cvt_pk_bf16_f32 v5, v218, v223
	ds_read_b64_tr_b16 v[234:235], v10 offset:27712
	ds_read_b64_tr_b16 v[236:237], v10 offset:28864
	s_waitcnt lgkmcnt(2)
	s_nop 0
	v_mfma_f32_32x32x16_bf16 v[32:47], v[6:9], v[2:5], v[32:47]
	ds_read_b64_tr_b16 v[6:7], v10 offset:29952
	ds_read_b64_tr_b16 v[8:9], v10 offset:31104
	s_waitcnt lgkmcnt(2)
	v_mfma_f32_32x32x16_bf16 v[16:31], v[234:237], v[2:5], v[16:31]
	v_cvt_pk_bf16_f32 v2, v173, v178
	v_cvt_pk_bf16_f32 v3, v192, v197
	v_cvt_pk_bf16_f32 v4, v207, v212
	v_cvt_pk_bf16_f32 v5, v219, v224
	ds_read_b64_tr_b16 v[234:235], v10 offset:30016
	ds_read_b64_tr_b16 v[236:237], v10 offset:31168
	s_waitcnt lgkmcnt(2)
	s_nop 0
	v_mfma_f32_32x32x16_bf16 v[32:47], v[6:9], v[2:5], v[32:47]
	s_waitcnt lgkmcnt(0)
	v_mfma_f32_32x32x16_bf16 v[16:31], v[234:237], v[2:5], v[16:31]
	s_and_b64 vcc, exec, s[46:47]
	s_lshl_b32 s10, s24, 6
	s_cbranch_vccz .LBB0_353
	s_branch .LBB0_354

; #define LAS __attribute__((address_space(3)))
; #define MFMA32(a, b, c) __builtin_amdgcn_mfma_f32_32x32x16_bf16((a), (b), (c), 0, 0, 0)
; __device__ __forceinline__ void attn_run(LAS unsigned char* lds, const Params& p, const bf16_t* P, bf16_t* Y, float* ssa, int l, int t0, int t1, int wave) {
;     ...
;             for (int T = 0; T < 6; ++T)
;                 if (T >= T0) {
;                     const int prow = 64 * ((T >> 1) == 0 ? sl0 : ((T >> 1) == 1 ? sl1 : sl2)) + 32 * (T & 1);
; #pragma unroll
;                     for (int s = 0; s < 2; ++s) {
;                         const bf16x8 xs = pack_step(st[T], s);
; #pragma unroll
;                         for (int dt = 0; dt < 2; ++dt) {
;                             const LAS bf16_t* vp = VT + (prow + 16 * s + 4 * h + ((lane & 15) >> 2)) * 72 + 32 * dt + 16 * ((lane >> 4) & 1) + 4 * (lane & 3);
;                             const s16x4 lo = __builtin_amdgcn_ds_read_tr16_b64_v4i16((LAS s16x4*)vp), hi = __builtin_amdgcn_ds_read_tr16_b64_v4i16((LAS s16x4*)(vp + 8 * 72));
;                             const bf16x8 pa = __builtin_shufflevector(lo, hi, 0, 1, 2, 3, 4, 5, 6, 7);
;                             o[dt] = MFMA32(pa, xs, o[dt]);
;                         }
;                     }
;                 }
.LBB0_360:
	v_add_u32_e32 v0, s29, v168
	v_mad_u64_u32 v[10:11], s[12:13], v0, s89, v[158:159]
	ds_read_b64_tr_b16 v[6:7], v10 offset:27648
	ds_read_b64_tr_b16 v[8:9], v10 offset:28800
	v_cvt_pk_bf16_f32 v2, v50, v75
	v_cvt_pk_bf16_f32 v3, v76, v77
	v_cvt_pk_bf16_f32 v4, v80, v171
	v_cvt_pk_bf16_f32 v5, v176, v195
	s_waitcnt lgkmcnt(0)
	s_nop 0
	v_mfma_f32_32x32x16_bf16 v[32:47], v[6:9], v[2:5], 0
	ds_read_b64_tr_b16 v[6:7], v10 offset:27712
	ds_read_b64_tr_b16 v[8:9], v10 offset:28864
	s_waitcnt lgkmcnt(0)
	v_mfma_f32_32x32x16_bf16 v[16:31], v[6:9], v[2:5], 0
	ds_read_b64_tr_b16 v[6:7], v10 offset:29952
	ds_read_b64_tr_b16 v[8:9], v10 offset:31104
	v_cvt_pk_bf16_f32 v2, v55, v210
	v_cvt_pk_bf16_f32 v3, v217, v222
	v_cvt_pk_bf16_f32 v4, v229, v230
	v_cvt_pk_bf16_f32 v5, v231, v232
	ds_read_b64_tr_b16 v[234:235], v10 offset:30016
	ds_read_b64_tr_b16 v[236:237], v10 offset:31168
	s_waitcnt lgkmcnt(2)
	s_nop 0
	v_mfma_f32_32x32x16_bf16 v[32:47], v[6:9], v[2:5], v[32:47]
	s_waitcnt lgkmcnt(0)
	v_mfma_f32_32x32x16_bf16 v[16:31], v[234:237], v[2:5], v[16:31]
	s_and_b64 vcc, exec, s[42:43]
	s_cbranch_vccnz .LBB0_351
	s_branch .LBB0_350

; #define LAS __attribute__((address_space(3)))
; #define MFMA32(a, b, c) __builtin_amdgcn_mfma_f32_32x32x16_bf16((a), (b), (c), 0, 0, 0)
; __device__ __forceinline__ void attn_run(LAS unsigned char* lds, const Params& p, const bf16_t* P, bf16_t* Y, float* ssa, int l, int t0, int t1, int wave) {
;     ...
;             for (int T = 0; T < 6; ++T)
;                 if (T >= T0) {
;                     const int prow = 64 * ((T >> 1) == 0 ? sl0 : ((T >> 1) == 1 ? sl1 : sl2)) + 32 * (T & 1);
; #pragma unroll
;                     for (int s = 0; s < 2; ++s) {
;                         const bf16x8 xs = pack_step(st[T], s);
; #pragma unroll
;                         for (int dt = 0; dt < 2; ++dt) {
;                             const LAS bf16_t* vp = VT + (prow + 16 * s + 4 * h + ((lane & 15) >> 2)) * 72 + 32 * dt + 16 * ((lane >> 4) & 1) + 4 * (lane & 3);
;                             const s16x4 lo = __builtin_amdgcn_ds_read_tr16_b64_v4i16((LAS s16x4*)vp), hi = __builtin_amdgcn_ds_read_tr16_b64_v4i16((LAS s16x4*)(vp + 8 * 72));
;                             const bf16x8 pa = __builtin_shufflevector(lo, hi, 0, 1, 2, 3, 4, 5, 6, 7);
;                             o[dt] = MFMA32(pa, xs, o[dt]);
;                         }
;                     }
;                 }
.LBB0_435:
	v_add_u32_e32 v0, s26, v169
	v_mad_u64_u32 v[10:11], s[12:13], v0, s89, v[158:159]
	ds_read_b64_tr_b16 v[6:7], v10 offset:27648
	ds_read_b64_tr_b16 v[8:9], v10 offset:28800
	v_cvt_pk_bf16_f32 v2, v179, v193
	v_cvt_pk_bf16_f32 v3, v198, v202
	v_cvt_pk_bf16_f32 v4, v213, v220
	v_cvt_pk_bf16_f32 v5, v225, v227
	ds_read_b64_tr_b16 v[234:235], v10 offset:27712
	ds_read_b64_tr_b16 v[236:237], v10 offset:28864
	s_waitcnt lgkmcnt(2)
	s_nop 0
	v_mfma_f32_32x32x16_bf16 v[32:47], v[6:9], v[2:5], v[32:47]
	ds_read_b64_tr_b16 v[6:7], v10 offset:29952
	ds_read_b64_tr_b16 v[8:9], v10 offset:31104
	s_waitcnt lgkmcnt(2)
	v_mfma_f32_32x32x16_bf16 v[16:31], v[234:237], v[2:5], v[16:31]
	v_cvt_pk_bf16_f32 v2, v180, v194
	v_cvt_pk_bf16_f32 v3, v199, v203
	v_cvt_pk_bf16_f32 v4, v214, v221
	v_cvt_pk_bf16_f32 v5, v226, v228
	ds_read_b64_tr_b16 v[234:235], v10 offset:30016
	ds_read_b64_tr_b16 v[236:237], v10 offset:31168
	s_waitcnt lgkmcnt(2)
	s_nop 0
	v_mfma_f32_32x32x16_bf16 v[32:47], v[6:9], v[2:5], v[32:47]
	s_waitcnt lgkmcnt(0)
	v_mfma_f32_32x32x16_bf16 v[16:31], v[234:237], v[2:5], v[16:31]

; #define LAS __attribute__((address_space(3)))
; #define MFMA32(a, b, c) __builtin_amdgcn_mfma_f32_32x32x16_bf16((a), (b), (c), 0, 0, 0)
; __device__ __forceinline__ void attn_run(LAS unsigned char* lds, const Params& p, const bf16_t* P, bf16_t* Y, float* ssa, int l, int t0, int t1, int wave) {
;     ...
;             for (int T = 0; T < 6; ++T)
;                 if (T >= T0) {
;                     const int prow = 64 * ((T >> 1) == 0 ? sl0 : ((T >> 1) == 1 ? sl1 : sl2)) + 32 * (T & 1);
; #pragma unroll
;                     for (int s = 0; s < 2; ++s) {
;                         const bf16x8 xs = pack_step(st[T], s);
; #pragma unroll
;                         for (int dt = 0; dt < 2; ++dt) {
;                             const LAS bf16_t* vp = VT + (prow + 16 * s + 4 * h + ((lane & 15) >> 2)) * 72 + 32 * dt + 16 * ((lane >> 4) & 1) + 4 * (lane & 3);
;                             const s16x4 lo = __builtin_amdgcn_ds_read_tr16_b64_v4i16((LAS s16x4*)vp), hi = __builtin_amdgcn_ds_read_tr16_b64_v4i16((LAS s16x4*)(vp + 8 * 72));
;                             const bf16x8 pa = __builtin_shufflevector(lo, hi, 0, 1, 2, 3, 4, 5, 6, 7);
;                             o[dt] = MFMA32(pa, xs, o[dt]);
;                         }
;                     }
;                 }
;             float ss = 0.f;
;             bf16_t* yp = Y + qrow * DM + head * 64 + 8 * h;
; #pragma unroll
;             for (int dt = 0; dt < 2; ++dt)
; #pragma unroll
;                 for (int pr = 0; pr < 2; ++pr) {
;                     float a[4], bq[4];
; #pragma unroll
;                     for (int k = 0; k < 4; ++k) { a[k] = o[dt][8 * pr + k] * inv; bq[k] = o[dt][8 * pr + 4 + k] * inv; }
;                     ss += ((a[0] * a[0] + a[1] * a[1]) + (a[2] * a[2] + a[3] * a[3])) + ((bq[0] * bq[0] + bq[1] * bq[1]) + (bq[2] * bq[2] + bq[3] * bq[3]));
; #pragma unroll
;                     for (int k = 0; k < 4; ++k) swap_halves(a[k], bq[k]);
;                     const u32x4 gw = gwv[2 * dt + pr];
;                     u32x4 w; w.x = pk2(a[0] * bf_lo(gw.x), a[1] * bf_hi(gw.x)); w.y = pk2(a[2] * bf_lo(gw.y), a[3] * bf_hi(gw.y));
;                     w.z = pk2(bq[0] * bf_lo(gw.z), bq[1] * bf_hi(gw.z)); w.w = pk2(bq[2] * bf_lo(gw.w), bq[3] * bf_hi(gw.w));
;                     *(u32x4*)(yp + 32 * dt + 16 * pr) = w;
;                 }
.LBB0_438:
	v_add_u32_e32 v0, s25, v169
	v_mad_u64_u32 v[10:11], s[12:13], v0, s89, v[158:159]
	ds_read_b64_tr_b16 v[6:7], v10 offset:27648
	ds_read_b64_tr_b16 v[8:9], v10 offset:28800
	v_cvt_pk_bf16_f32 v2, v94, v97
	v_cvt_pk_bf16_f32 v3, v174, v181
	v_cvt_pk_bf16_f32 v4, v200, v204
	v_cvt_pk_bf16_f32 v5, v208, v215
	ds_read_b64_tr_b16 v[234:235], v10 offset:27712
	ds_read_b64_tr_b16 v[236:237], v10 offset:28864
	s_waitcnt lgkmcnt(2)
	s_nop 0
	v_mfma_f32_32x32x16_bf16 v[32:47], v[6:9], v[2:5], v[32:47]
	ds_read_b64_tr_b16 v[6:7], v10 offset:29952
	ds_read_b64_tr_b16 v[8:9], v10 offset:31104
	s_waitcnt lgkmcnt(2)
	v_mfma_f32_32x32x16_bf16 v[16:31], v[234:237], v[2:5], v[16:31]
	v_cvt_pk_bf16_f32 v2, v95, v163
	v_cvt_pk_bf16_f32 v3, v175, v182
	v_cvt_pk_bf16_f32 v4, v201, v205
	v_cvt_pk_bf16_f32 v5, v209, v216
	ds_read_b64_tr_b16 v[234:235], v10 offset:30016
	ds_read_b64_tr_b16 v[236:237], v10 offset:31168
	s_waitcnt lgkmcnt(2)
	s_nop 0
	v_mfma_f32_32x32x16_bf16 v[32:47], v[6:9], v[2:5], v[32:47]
	s_waitcnt lgkmcnt(0)
	v_mfma_f32_32x32x16_bf16 v[16:31], v[234:237], v[2:5], v[16:31]
.LBB0_439:
	v_add_u32_e32 v6, s24, v168
	v_sub_f32_e32 v2, v66, v68
	v_mad_u64_u32 v[10:11], s[12:13], v6, s89, v[158:159]
	v_exp_f32_e32 v2, v2
	ds_read_b64_tr_b16 v[6:7], v10 offset:27648
	ds_read_b64_tr_b16 v[8:9], v10 offset:28800
	s_waitcnt lgkmcnt(2)
	v_add_f32_e32 v0, v69, v70
	v_cvt_pk_bf16_f32 v3, v63, v79
	v_add_f32_e32 v0, v2, v0
	v_cvt_pk_bf16_f32 v2, v56, v60
	v_cvt_pk_bf16_f32 v4, v144, v145
	v_cvt_pk_bf16_f32 v5, v142, v143
	s_lshl_b32 s44, s10, 1
	s_waitcnt lgkmcnt(0)
	v_mfma_f32_32x32x16_bf16 v[32:47], v[6:9], v[2:5], v[32:47]
	ds_read_b64_tr_b16 v[6:7], v10 offset:27712
	ds_read_b64_tr_b16 v[8:9], v10 offset:28864
	ds_read_b64_tr_b16 v[234:235], v10 offset:29952
	ds_read_b64_tr_b16 v[236:237], v10 offset:31104
	s_waitcnt lgkmcnt(2)
	v_mfma_f32_32x32x16_bf16 v[16:31], v[6:9], v[2:5], v[16:31]
	v_cvt_pk_bf16_f32 v2, v59, v64
	v_cvt_pk_bf16_f32 v3, v78, v96
	v_cvt_pk_bf16_f32 v4, v92, v93
	v_cvt_pk_bf16_f32 v5, v90, v91
	ds_read_b64_tr_b16 v[6:7], v10 offset:30016
	ds_read_b64_tr_b16 v[8:9], v10 offset:31168
	s_waitcnt lgkmcnt(2)
	s_nop 0
	v_mfma_f32_32x32x16_bf16 v[32:47], v[234:237], v[2:5], v[32:47]
	s_waitcnt lgkmcnt(0)
	v_mfma_f32_32x32x16_bf16 v[16:31], v[6:9], v[2:5], v[16:31]
	v_add_u32_e32 v6, s24, v169
	v_mad_u64_u32 v[10:11], s[12:13], v6, s89, v[158:159]
	ds_read_b64_tr_b16 v[6:7], v10 offset:27648
	ds_read_b64_tr_b16 v[8:9], v10 offset:28800
	v_cvt_pk_bf16_f32 v2, v52, v54
	v_cvt_pk_bf16_f32 v3, v57, v61
	v_cvt_pk_bf16_f32 v4, v81, v84
	v_cvt_pk_bf16_f32 v5, v82, v83
	ds_read_b64_tr_b16 v[234:235], v10 offset:27712
	ds_read_b64_tr_b16 v[236:237], v10 offset:28864
	s_waitcnt lgkmcnt(2)
	s_nop 0
	v_mfma_f32_32x32x16_bf16 v[32:47], v[6:9], v[2:5], v[32:47]
	ds_read_b64_tr_b16 v[6:7], v10 offset:29952
	ds_read_b64_tr_b16 v[8:9], v10 offset:31104
	s_waitcnt lgkmcnt(2)
	v_mfma_f32_32x32x16_bf16 v[16:31], v[234:237], v[2:5], v[16:31]
	v_cvt_pk_bf16_f32 v2, v48, v49
	v_cvt_pk_bf16_f32 v3, v51, v53
	v_cvt_pk_bf16_f32 v4, v58, v62
	v_cvt_pk_bf16_f32 v5, v65, v67
	ds_read_b64_tr_b16 v[234:235], v10 offset:30016
	ds_read_b64_tr_b16 v[236:237], v10 offset:31168
	s_waitcnt lgkmcnt(2)
	s_nop 0
	v_mfma_f32_32x32x16_bf16 v[32:47], v[6:9], v[2:5], v[32:47]
	s_waitcnt lgkmcnt(0)
	v_mfma_f32_32x32x16_bf16 v[16:31], v[234:237], v[2:5], v[16:31]
	v_div_scale_f32 v2, s[12:13], v0, v0, 1.0
	v_rcp_f32_e32 v3, v2
	s_nop 0
	v_fma_f32 v4, -v2, v3, 1.0
	v_fmac_f32_e32 v3, v4, v3
	v_div_scale_f32 v4, vcc, 1.0, v0, 1.0
	v_mul_f32_e32 v5, v4, v3
	v_fma_f32 v6, -v2, v5, v4
	v_fmac_f32_e32 v5, v6, v3
	v_fma_f32 v2, -v2, v5, v4
	v_div_fmas_f32 v2, v2, v3, v5
	v_div_fixup_f32 v0, v2, v0, 1.0
	v_mul_f32_e32 v5, v0, v33
	v_mul_f32_e32 v9, v0, v35
	v_mul_f32_e32 v4, v0, v32
	v_mul_f32_e32 v8, v0, v34
	v_mul_f32_e32 v12, v5, v5
	v_mul_f32_e32 v13, v9, v9
	v_mul_f32_e32 v7, v0, v37
	v_mul_f32_e32 v11, v0, v39
	v_fmac_f32_e32 v12, v4, v4
	v_fmac_f32_e32 v13, v8, v8
	v_mul_f32_e32 v6, v0, v36
	v_mul_f32_e32 v10, v0, v38
	v_add_f32_e32 v12, v12, v13
	v_mul_f32_e32 v13, v7, v7
	v_mul_f32_e32 v14, v11, v11
	v_fmac_f32_e32 v13, v6, v6
	v_fmac_f32_e32 v14, v10, v10
	v_add_f32_e32 v13, v13, v14
	v_permlane32_swap_b32_e32 v4, v6
	v_permlane32_swap_b32_e32 v5, v7
	v_add_f32_e32 v14, v13, v12
	v_permlane32_swap_b32_e32 v8, v10
	v_permlane32_swap_b32_e32 v9, v11
	v_lshlrev_b32_e32 v12, 16, v134
	v_and_b32_e32 v13, 0xffff0000, v134
	v_pk_mul_f32 v[4:5], v[12:13], v[4:5]
	v_lshlrev_b32_e32 v12, 16, v135
	v_and_b32_e32 v13, 0xffff0000, v135
	v_pk_mul_f32 v[8:9], v[12:13], v[8:9]
	v_lshlrev_b64 v[2:3], 12, v[164:165]
	v_cvt_pk_bf16_f32 v4, v4, v5
	v_cvt_pk_bf16_f32 v5, v8, v9
	v_lshlrev_b32_e32 v8, 16, v136
	v_and_b32_e32 v9, 0xffff0000, v136
	v_lshl_add_u64 v[2:3], s[36:37], 0, v[2:3]
	v_pk_mul_f32 v[6:7], v[8:9], v[6:7]
	v_lshlrev_b32_e32 v8, 16, v137
	v_and_b32_e32 v9, 0xffff0000, v137
	v_lshl_add_u64 v[2:3], v[2:3], 0, s[44:45]
	v_pk_mul_f32 v[8:9], v[8:9], v[10:11]
	v_lshl_add_u64 v[2:3], v[156:157], 1, v[2:3]
	v_cvt_pk_bf16_f32 v6, v6, v7
	v_cvt_pk_bf16_f32 v7, v8, v9
	global_store_dwordx4 v[2:3], v[4:7], off
	v_mul_f32_e32 v9, v0, v43
	v_mul_f32_e32 v8, v0, v42
	v_mul_f32_e32 v5, v0, v41
	v_mul_f32_e32 v4, v0, v40
	v_mul_f32_e32 v12, v5, v5
	v_mul_f32_e32 v13, v9, v9
; #define LAS __attribute__((address_space(3)))
; __device__ __forceinline__ void attn_run(LAS unsigned char* lds, const Params& p, const bf16_t* P, bf16_t* Y, float* ssa, int l, int t0, int t1, int wave) {
;     ...
;             for (int T = 0; T < 6; ++T)
;                 if (T >= T0) {
;                     const int prow = 64 * ((T >> 1) == 0 ? sl0 : ((T >> 1) == 1 ? sl1 : sl2)) + 32 * (T & 1);
; #pragma unroll
;                     for (int s = 0; s < 2; ++s) {
;                         const bf16x8 xs = pack_step(st[T], s);
; #pragma unroll
;                         for (int dt = 0; dt < 2; ++dt) {
;                             const LAS bf16_t* vp = VT + (prow + 16 * s + 4 * h + ((lane & 15) >> 2)) * 72 + 32 * dt + 16 * ((lane >> 4) & 1) + 4 * (lane & 3);
;                             const s16x4 lo = __builtin_amdgcn_ds_read_tr16_b64_v4i16((LAS s16x4*)vp), hi = __builtin_amdgcn_ds_read_tr16_b64_v4i16((LAS s16x4*)(vp + 8 * 72));
;                             const bf16x8 pa = __builtin_shufflevector(lo, hi, 0, 1, 2, 3, 4, 5, 6, 7);
;                             o[dt] = MFMA32(pa, xs, o[dt]);
;                         }
;                     }
;                 }
;             float ss = 0.f;
;             bf16_t* yp = Y + qrow * DM + head * 64 + 8 * h;
; #pragma unroll
;             for (int dt = 0; dt < 2; ++dt)
; #pragma unroll
;                 for (int pr = 0; pr < 2; ++pr) {
;                     float a[4], bq[4];
; #pragma unroll
;                     for (int k = 0; k < 4; ++k) { a[k] = o[dt][8 * pr + k] * inv; bq[k] = o[dt][8 * pr + 4 + k] * inv; }
;                     ss += ((a[0] * a[0] + a[1] * a[1]) + (a[2] * a[2] + a[3] * a[3])) + ((bq[0] * bq[0] + bq[1] * bq[1]) + (bq[2] * bq[2] + bq[3] * bq[3]));
; #pragma unroll
;                     for (int k = 0; k < 4; ++k) swap_halves(a[k], bq[k]);
;                     const u32x4 gw = gwv[2 * dt + pr];
;                     u32x4 w; w.x = pk2(a[0] * bf_lo(gw.x), a[1] * bf_hi(gw.x)); w.y = pk2(a[2] * bf_lo(gw.y), a[3] * bf_hi(gw.y));
;                     w.z = pk2(bq[0] * bf_lo(gw.z), bq[1] * bf_hi(gw.z)); w.w = pk2(bq[2] * bf_lo(gw.w), bq[3] * bf_hi(gw.w));
;                     *(u32x4*)(yp + 32 * dt + 16 * pr) = w;
;                 }
;             ss += __shfl_xor(ss, 32);
;             if (h == 0) ssa[qrow * 16 + head] = ss;
	v_mul_f32_e32 v7, v0, v45
	v_mul_f32_e32 v11, v0, v47
	v_fmac_f32_e32 v12, v4, v4
	v_fmac_f32_e32 v13, v8, v8
	v_mul_f32_e32 v6, v0, v44
	v_mul_f32_e32 v10, v0, v46
	v_add_f32_e32 v12, v12, v13
	v_mul_f32_e32 v13, v7, v7
	v_mul_f32_e32 v15, v11, v11
	v_fmac_f32_e32 v13, v6, v6
	v_fmac_f32_e32 v15, v10, v10
	v_add_f32_e32 v13, v13, v15
	v_add_f32_e32 v12, v13, v12
	v_permlane32_swap_b32_e32 v4, v6
	v_permlane32_swap_b32_e32 v5, v7
	v_permlane32_swap_b32_e32 v8, v10
	v_permlane32_swap_b32_e32 v9, v11
	v_add_f32_e32 v14, v14, v12
	v_lshlrev_b32_e32 v12, 16, v130
	v_and_b32_e32 v13, 0xffff0000, v130
	v_pk_mul_f32 v[4:5], v[12:13], v[4:5]
	v_lshlrev_b32_e32 v12, 16, v131
	v_and_b32_e32 v13, 0xffff0000, v131
	v_pk_mul_f32 v[8:9], v[12:13], v[8:9]
	v_cvt_pk_bf16_f32 v4, v4, v5
	v_cvt_pk_bf16_f32 v5, v8, v9
	v_lshlrev_b32_e32 v8, 16, v132
	v_and_b32_e32 v9, 0xffff0000, v132
	v_pk_mul_f32 v[6:7], v[8:9], v[6:7]
	v_lshlrev_b32_e32 v8, 16, v133
	v_and_b32_e32 v9, 0xffff0000, v133
	v_pk_mul_f32 v[8:9], v[8:9], v[10:11]
	v_cvt_pk_bf16_f32 v6, v6, v7
	v_cvt_pk_bf16_f32 v7, v8, v9
	global_store_dwordx4 v[2:3], v[4:7], off offset:32
	v_mul_f32_e32 v9, v0, v19
	v_mul_f32_e32 v8, v0, v18
	v_mul_f32_e32 v5, v0, v17
	v_mul_f32_e32 v4, v0, v16
	v_mul_f32_e32 v12, v5, v5
	v_mul_f32_e32 v13, v9, v9
	v_mul_f32_e32 v7, v0, v21
	v_mul_f32_e32 v11, v0, v23
	v_fmac_f32_e32 v12, v4, v4
	v_fmac_f32_e32 v13, v8, v8
	v_mul_f32_e32 v6, v0, v20
	v_mul_f32_e32 v10, v0, v22
	v_add_f32_e32 v12, v12, v13
	v_mul_f32_e32 v13, v7, v7
	v_mul_f32_e32 v15, v11, v11
	v_fmac_f32_e32 v13, v6, v6
	v_fmac_f32_e32 v15, v10, v10
	v_add_f32_e32 v13, v13, v15
	v_add_f32_e32 v12, v13, v12
	v_permlane32_swap_b32_e32 v4, v6
	v_permlane32_swap_b32_e32 v5, v7
	v_permlane32_swap_b32_e32 v8, v10
	v_permlane32_swap_b32_e32 v9, v11
	v_add_f32_e32 v14, v14, v12
	v_lshlrev_b32_e32 v12, 16, v126
	v_and_b32_e32 v13, 0xffff0000, v126
	v_pk_mul_f32 v[4:5], v[12:13], v[4:5]
	v_lshlrev_b32_e32 v12, 16, v127
	v_and_b32_e32 v13, 0xffff0000, v127
	v_pk_mul_f32 v[8:9], v[12:13], v[8:9]
	v_cvt_pk_bf16_f32 v4, v4, v5
	v_cvt_pk_bf16_f32 v5, v8, v9
	v_lshlrev_b32_e32 v8, 16, v128
	v_and_b32_e32 v9, 0xffff0000, v128
	v_pk_mul_f32 v[6:7], v[8:9], v[6:7]
	v_lshlrev_b32_e32 v8, 16, v129
	v_and_b32_e32 v9, 0xffff0000, v129
	v_pk_mul_f32 v[8:9], v[8:9], v[10:11]
	v_cvt_pk_bf16_f32 v6, v6, v7
	v_cvt_pk_bf16_f32 v7, v8, v9
	global_store_dwordx4 v[2:3], v[4:7], off offset:64
	v_mul_f32_e32 v9, v0, v27
	v_mul_f32_e32 v8, v0, v26
	v_mul_f32_e32 v5, v0, v25
	v_mul_f32_e32 v4, v0, v24
	v_mul_f32_e32 v6, v0, v28
	v_mul_f32_e32 v7, v0, v29
	v_mul_f32_e32 v10, v0, v30
	v_mul_f32_e32 v11, v0, v31
	v_mul_f32_e32 v0, v5, v5
	v_mul_f32_e32 v12, v9, v9
	v_fmac_f32_e32 v0, v4, v4
	v_fmac_f32_e32 v12, v8, v8
	v_add_f32_e32 v0, v0, v12
	v_mul_f32_e32 v12, v7, v7
	v_mul_f32_e32 v13, v11, v11
	v_fmac_f32_e32 v12, v6, v6
	v_fmac_f32_e32 v13, v10, v10
	v_add_f32_e32 v12, v12, v13
	v_permlane32_swap_b32_e32 v4, v6
	v_permlane32_swap_b32_e32 v5, v7
	v_add_f32_e32 v0, v12, v0
	v_permlane32_swap_b32_e32 v8, v10
	v_permlane32_swap_b32_e32 v9, v11
	v_lshlrev_b32_e32 v12, 16, v122
	v_and_b32_e32 v13, 0xffff0000, v122
	v_pk_mul_f32 v[4:5], v[12:13], v[4:5]
	v_lshlrev_b32_e32 v12, 16, v123
	v_and_b32_e32 v13, 0xffff0000, v123
	v_pk_mul_f32 v[8:9], v[12:13], v[8:9]
	v_cvt_pk_bf16_f32 v4, v4, v5
	v_cvt_pk_bf16_f32 v5, v8, v9
	v_lshlrev_b32_e32 v8, 16, v124
	v_and_b32_e32 v9, 0xffff0000, v124
	v_pk_mul_f32 v[6:7], v[8:9], v[6:7]
	v_lshlrev_b32_e32 v8, 16, v125
	v_and_b32_e32 v9, 0xffff0000, v125
	v_pk_mul_f32 v[8:9], v[8:9], v[10:11]
	v_add_f32_e32 v0, v0, v14
	v_cvt_pk_bf16_f32 v6, v6, v7
	v_cvt_pk_bf16_f32 v7, v8, v9
	global_store_dwordx4 v[2:3], v[4:7], off offset:96
	ds_bpermute_b32 v2, v167, v0
	s_and_saveexec_b64 s[10:11], s[40:41]
	s_cbranch_execz .LBB0_409
	v_readlane_b32 s4, v253, 15
	v_lshlrev_b64 v[4:5], 6, v[164:165]
	v_readlane_b32 s5, v253, 16
	s_lshl_b32 s44, s23, 2
	s_waitcnt lgkmcnt(0)
	v_add_f32_e32 v0, v0, v2
	v_lshl_add_u64 v[4:5], s[4:5], 0, v[4:5]
	v_lshl_add_u64 v[4:5], v[4:5], 0, s[44:45]
	global_store_dword v[4:5], v0, off
	s_branch .LBB0_409
.LBB0_441:
	v_add_u32_e32 v0, s25, v168
	v_mad_u64_u32 v[10:11], s[10:11], v0, s89, v[158:159]
	ds_read_b64_tr_b16 v[6:7], v10 offset:27648
	ds_read_b64_tr_b16 v[8:9], v10 offset:28800
	v_cvt_pk_bf16_f32 v2, v172, v177
	v_cvt_pk_bf16_f32 v3, v183, v196
	v_cvt_pk_bf16_f32 v4, v206, v211
	v_cvt_pk_bf16_f32 v5, v218, v223
	ds_read_b64_tr_b16 v[234:235], v10 offset:27712
	ds_read_b64_tr_b16 v[236:237], v10 offset:28864
	s_waitcnt lgkmcnt(2)
	s_nop 0
	v_mfma_f32_32x32x16_bf16 v[32:47], v[6:9], v[2:5], v[32:47]
	ds_read_b64_tr_b16 v[6:7], v10 offset:29952
	ds_read_b64_tr_b16 v[8:9], v10 offset:31104
	s_waitcnt lgkmcnt(2)
	v_mfma_f32_32x32x16_bf16 v[16:31], v[234:237], v[2:5], v[16:31]
	v_cvt_pk_bf16_f32 v2, v173, v178
	v_cvt_pk_bf16_f32 v3, v192, v197
	v_cvt_pk_bf16_f32 v4, v207, v212
	v_cvt_pk_bf16_f32 v5, v219, v224
	ds_read_b64_tr_b16 v[234:235], v10 offset:30016
	ds_read_b64_tr_b16 v[236:237], v10 offset:31168
	s_waitcnt lgkmcnt(2)
	s_nop 0
	v_mfma_f32_32x32x16_bf16 v[32:47], v[6:9], v[2:5], v[32:47]
	s_waitcnt lgkmcnt(0)
	v_mfma_f32_32x32x16_bf16 v[16:31], v[234:237], v[2:5], v[16:31]
	s_and_b64 vcc, exec, s[46:47]
	s_lshl_b32 s10, s23, 6
	s_cbranch_vccz .LBB0_438
	s_branch .LBB0_439

; #define LAS __attribute__((address_space(3)))
; #define MFMA32(a, b, c) __builtin_amdgcn_mfma_f32_32x32x16_bf16((a), (b), (c), 0, 0, 0)
; __device__ __forceinline__ void attn_run(LAS unsigned char* lds, const Params& p, const bf16_t* P, bf16_t* Y, float* ssa, int l, int t0, int t1, int wave) {
;     ...
;             for (int T = 0; T < 6; ++T)
;                 if (T >= T0) {
;                     const int prow = 64 * ((T >> 1) == 0 ? sl0 : ((T >> 1) == 1 ? sl1 : sl2)) + 32 * (T & 1);
; #pragma unroll
;                     for (int s = 0; s < 2; ++s) {
;                         const bf16x8 xs = pack_step(st[T], s);
; #pragma unroll
;                         for (int dt = 0; dt < 2; ++dt) {
;                             const LAS bf16_t* vp = VT + (prow + 16 * s + 4 * h + ((lane & 15) >> 2)) * 72 + 32 * dt + 16 * ((lane >> 4) & 1) + 4 * (lane & 3);
;                             const s16x4 lo = __builtin_amdgcn_ds_read_tr16_b64_v4i16((LAS s16x4*)vp), hi = __builtin_amdgcn_ds_read_tr16_b64_v4i16((LAS s16x4*)(vp + 8 * 72));
;                             const bf16x8 pa = __builtin_shufflevector(lo, hi, 0, 1, 2, 3, 4, 5, 6, 7);
;                             o[dt] = MFMA32(pa, xs, o[dt]);
;                         }
;                     }
;                 }
.LBB0_445:
	v_add_u32_e32 v0, s26, v168
	v_mad_u64_u32 v[10:11], s[12:13], v0, s89, v[158:159]
	ds_read_b64_tr_b16 v[6:7], v10 offset:27648
	ds_read_b64_tr_b16 v[8:9], v10 offset:28800
	v_cvt_pk_bf16_f32 v2, v50, v75
	v_cvt_pk_bf16_f32 v3, v76, v77
	v_cvt_pk_bf16_f32 v4, v80, v171
	v_cvt_pk_bf16_f32 v5, v176, v195
	s_waitcnt lgkmcnt(0)
	s_nop 0
	v_mfma_f32_32x32x16_bf16 v[32:47], v[6:9], v[2:5], 0
	ds_read_b64_tr_b16 v[6:7], v10 offset:27712
	ds_read_b64_tr_b16 v[8:9], v10 offset:28864
	s_waitcnt lgkmcnt(0)
	v_mfma_f32_32x32x16_bf16 v[16:31], v[6:9], v[2:5], 0
	ds_read_b64_tr_b16 v[6:7], v10 offset:29952
	ds_read_b64_tr_b16 v[8:9], v10 offset:31104
	v_cvt_pk_bf16_f32 v2, v55, v210
	v_cvt_pk_bf16_f32 v3, v217, v222
	v_cvt_pk_bf16_f32 v4, v229, v230
	v_cvt_pk_bf16_f32 v5, v231, v232
	ds_read_b64_tr_b16 v[234:235], v10 offset:30016
	ds_read_b64_tr_b16 v[236:237], v10 offset:31168
	s_waitcnt lgkmcnt(2)
	s_nop 0
	v_mfma_f32_32x32x16_bf16 v[32:47], v[6:9], v[2:5], v[32:47]
	s_waitcnt lgkmcnt(0)
	v_mfma_f32_32x32x16_bf16 v[16:31], v[234:237], v[2:5], v[16:31]
	s_and_b64 vcc, exec, s[42:43]
	s_cbranch_vccnz .LBB0_436
	s_branch .LBB0_435
